# v18 + batched (non-serialized) NSA selected/window branch epilogues and MLA output epilogue: loads/permutes/stores issued in groups instead of one round trip per element
# speedup vs baseline: 1.0144x; 1.0075x over previous
.LBB0_1994:
	s_or_b64 exec, exec, s[0:1]
	v_readlane_b32 s0, v255, 1
	v_lshl_add_u32 v4, v220, 2, s6
	v_ashrrev_i32_e32 v195, 31, v194
	v_readlane_b32 s1, v255, 2
	v_ashrrev_i32_e32 v5, 31, v4
	v_lshlrev_b64 v[6:7], 9, v[4:5]
	v_lshl_add_u64 v[2:3], v[194:195], 2, s[0:1]
	s_waitcnt lgkmcnt(0)
	v_lshl_add_u64 v[6:7], v[2:3], 0, v[6:7]
	v_lshl_add_u32 v0, v220, 4, s15
	ds_read_b128 v[104:107], v0
	ds_read_b128 v[108:111], v0 offset:32
	ds_read_b128 v[112:115], v0 offset:64
	ds_read_b128 v[116:119], v0 offset:96
	v_add_co_u32_e32 v98, vcc, 0x1000, v6
	s_nop 1
	v_addc_co_u32_e32 v99, vcc, 0, v7, vcc
	v_add_co_u32_e32 v100, vcc, 0x2000, v6
	s_nop 1
	v_addc_co_u32_e32 v101, vcc, 0, v7, vcc
	v_add_co_u32_e32 v102, vcc, 0x3000, v6
	s_nop 1
	v_addc_co_u32_e32 v103, vcc, 0, v7, vcc
	global_load_dword v144, v[6:7], off
	global_load_dword v145, v[6:7], off offset:128
	global_load_dword v146, v[6:7], off offset:256
	global_load_dword v147, v[6:7], off offset:384
	global_load_dword v148, v[6:7], off offset:512
	global_load_dword v149, v[6:7], off offset:640
	global_load_dword v150, v[6:7], off offset:768
	global_load_dword v151, v[6:7], off offset:896
	global_load_dword v152, v[6:7], off offset:1024
	global_load_dword v153, v[6:7], off offset:1152
	global_load_dword v154, v[6:7], off offset:1280
	global_load_dword v155, v[6:7], off offset:1408
	global_load_dword v156, v[6:7], off offset:1536
	global_load_dword v157, v[6:7], off offset:1664
	global_load_dword v158, v[6:7], off offset:1792
	global_load_dword v159, v[6:7], off offset:1920
	global_load_dword v160, v[98:99], off
	global_load_dword v161, v[98:99], off offset:128
	global_load_dword v162, v[98:99], off offset:256
	global_load_dword v163, v[98:99], off offset:384
	global_load_dword v164, v[98:99], off offset:512
	global_load_dword v165, v[98:99], off offset:640
	global_load_dword v166, v[98:99], off offset:768
	global_load_dword v167, v[98:99], off offset:896
	global_load_dword v168, v[98:99], off offset:1024
	global_load_dword v169, v[98:99], off offset:1152
	global_load_dword v170, v[98:99], off offset:1280
	global_load_dword v171, v[98:99], off offset:1408
	global_load_dword v172, v[98:99], off offset:1536
	global_load_dword v173, v[98:99], off offset:1664
	global_load_dword v174, v[98:99], off offset:1792
	global_load_dword v175, v[98:99], off offset:1920
	global_load_dword v176, v[100:101], off
	global_load_dword v177, v[100:101], off offset:128
	global_load_dword v178, v[100:101], off offset:256
	global_load_dword v179, v[100:101], off offset:384
	global_load_dword v180, v[100:101], off offset:512
	global_load_dword v181, v[100:101], off offset:640
	global_load_dword v182, v[100:101], off offset:768
	global_load_dword v183, v[100:101], off offset:896
	global_load_dword v184, v[100:101], off offset:1024
	global_load_dword v185, v[100:101], off offset:1152
	global_load_dword v186, v[100:101], off offset:1280
	global_load_dword v187, v[100:101], off offset:1408
	global_load_dword v188, v[100:101], off offset:1536
	global_load_dword v189, v[100:101], off offset:1664
	global_load_dword v190, v[100:101], off offset:1792
	global_load_dword v191, v[100:101], off offset:1920
	global_load_dword v200, v[102:103], off
	global_load_dword v201, v[102:103], off offset:128
	global_load_dword v202, v[102:103], off offset:256
	global_load_dword v203, v[102:103], off offset:384
	global_load_dword v204, v[102:103], off offset:512
	global_load_dword v205, v[102:103], off offset:640
	global_load_dword v206, v[102:103], off offset:768
	global_load_dword v207, v[102:103], off offset:896
	global_load_dword v208, v[102:103], off offset:1024
	global_load_dword v209, v[102:103], off offset:1152
	global_load_dword v210, v[102:103], off offset:1280
	global_load_dword v211, v[102:103], off offset:1408
	global_load_dword v212, v[102:103], off offset:1536
	global_load_dword v213, v[102:103], off offset:1664
	global_load_dword v214, v[102:103], off offset:1792
	global_load_dword v215, v[102:103], off offset:1920
	s_lshl_b64 s[0:1], s[2:3], 1
	v_readlane_b32 s2, v254, 55
	s_add_u32 s6, s2, s0
	v_readlane_b32 s2, v254, 56
	s_addc_u32 s7, s2, s1
	v_readlane_b32 s2, v254, 57
	s_add_u32 s8, s2, s0
	v_readlane_b32 s0, v254, 58
	s_addc_u32 s9, s0, s1
	s_lshr_b32 s16, s90, 6
	v_sub_u32_e64 v17, s16, 8 clamp
	v_lshlrev_b32_e32 v10, 14, v17
	v_mov_b32_e32 v11, v1
	v_readfirstlane_b32 s0, v17
	s_sub_i32 s18, s16, s0
	s_waitcnt vmcnt(32) lgkmcnt(0)
	v_fmac_f32_e32 v144, v80, v104
	v_fmac_f32_e32 v145, v64, v104
	v_fmac_f32_e32 v146, v48, v104
	v_fmac_f32_e32 v147, v32, v104
	v_fmac_f32_e32 v148, v81, v105
	v_fmac_f32_e32 v149, v65, v105
	v_fmac_f32_e32 v150, v49, v105
	v_fmac_f32_e32 v151, v33, v105
	v_fmac_f32_e32 v152, v82, v106
	v_fmac_f32_e32 v153, v66, v106
	v_fmac_f32_e32 v154, v50, v106
	v_fmac_f32_e32 v155, v34, v106
	v_fmac_f32_e32 v156, v83, v107
	v_fmac_f32_e32 v157, v67, v107
	v_fmac_f32_e32 v158, v51, v107
	v_fmac_f32_e32 v159, v35, v107
	v_fmac_f32_e32 v160, v84, v108
	v_fmac_f32_e32 v161, v68, v108
	v_fmac_f32_e32 v162, v52, v108
	v_fmac_f32_e32 v163, v36, v108
	v_fmac_f32_e32 v164, v85, v109
	v_fmac_f32_e32 v165, v69, v109
	v_fmac_f32_e32 v166, v53, v109
	v_fmac_f32_e32 v167, v37, v109
	v_fmac_f32_e32 v168, v86, v110
	v_fmac_f32_e32 v169, v70, v110
	v_fmac_f32_e32 v170, v54, v110
	v_fmac_f32_e32 v171, v38, v110
	v_fmac_f32_e32 v172, v87, v111
	v_fmac_f32_e32 v173, v71, v111
	v_fmac_f32_e32 v174, v55, v111
	v_fmac_f32_e32 v175, v39, v111
	global_store_dword v[6:7], v144, off
	global_store_dword v[6:7], v145, off offset:128
	global_store_dword v[6:7], v146, off offset:256
	global_store_dword v[6:7], v147, off offset:384
	global_store_dword v[6:7], v148, off offset:512
	global_store_dword v[6:7], v149, off offset:640
	global_store_dword v[6:7], v150, off offset:768
	global_store_dword v[6:7], v151, off offset:896
	global_store_dword v[6:7], v152, off offset:1024
	global_store_dword v[6:7], v153, off offset:1152
	global_store_dword v[6:7], v154, off offset:1280
	global_store_dword v[6:7], v155, off offset:1408
	global_store_dword v[6:7], v156, off offset:1536
	global_store_dword v[6:7], v157, off offset:1664
	global_store_dword v[6:7], v158, off offset:1792
	global_store_dword v[6:7], v159, off offset:1920
	global_store_dword v[98:99], v160, off
	global_store_dword v[98:99], v161, off offset:128
	global_store_dword v[98:99], v162, off offset:256
	global_store_dword v[98:99], v163, off offset:384
	global_store_dword v[98:99], v164, off offset:512
	global_store_dword v[98:99], v165, off offset:640
	global_store_dword v[98:99], v166, off offset:768
	global_store_dword v[98:99], v167, off offset:896
	global_store_dword v[98:99], v168, off offset:1024
	global_store_dword v[98:99], v169, off offset:1152
	global_store_dword v[98:99], v170, off offset:1280
	global_store_dword v[98:99], v171, off offset:1408
	global_store_dword v[98:99], v172, off offset:1536
	global_store_dword v[98:99], v173, off offset:1664
	global_store_dword v[98:99], v174, off offset:1792
	global_store_dword v[98:99], v175, off offset:1920
	s_waitcnt vmcnt(32)
	v_fmac_f32_e32 v176, v88, v112
	v_fmac_f32_e32 v177, v72, v112
	v_fmac_f32_e32 v178, v56, v112
	v_fmac_f32_e32 v179, v40, v112
	v_fmac_f32_e32 v180, v89, v113
	v_fmac_f32_e32 v181, v73, v113
	v_fmac_f32_e32 v182, v57, v113
	v_fmac_f32_e32 v183, v41, v113
	v_fmac_f32_e32 v184, v90, v114
	v_fmac_f32_e32 v185, v74, v114
	v_fmac_f32_e32 v186, v58, v114
	v_fmac_f32_e32 v187, v42, v114
	v_fmac_f32_e32 v188, v91, v115
	v_fmac_f32_e32 v189, v75, v115
	v_fmac_f32_e32 v190, v59, v115
	v_fmac_f32_e32 v191, v43, v115
	v_fmac_f32_e32 v200, v92, v116
	v_fmac_f32_e32 v201, v76, v116
	v_fmac_f32_e32 v202, v60, v116
	v_fmac_f32_e32 v203, v44, v116
	v_fmac_f32_e32 v204, v93, v117
	v_fmac_f32_e32 v205, v77, v117
	v_fmac_f32_e32 v206, v61, v117
	v_fmac_f32_e32 v207, v45, v117
	v_fmac_f32_e32 v208, v94, v118
	v_fmac_f32_e32 v209, v78, v118
	v_fmac_f32_e32 v210, v62, v118
	v_fmac_f32_e32 v211, v46, v118
	v_fmac_f32_e32 v212, v95, v119
	v_fmac_f32_e32 v213, v79, v119
	v_fmac_f32_e32 v214, v63, v119
	v_fmac_f32_e32 v215, v47, v119
	global_store_dword v[100:101], v176, off
	global_store_dword v[100:101], v177, off offset:128
	global_store_dword v[100:101], v178, off offset:256
	global_store_dword v[100:101], v179, off offset:384
	global_store_dword v[100:101], v180, off offset:512
	global_store_dword v[100:101], v181, off offset:640
	global_store_dword v[100:101], v182, off offset:768
	global_store_dword v[100:101], v183, off offset:896
	global_store_dword v[100:101], v184, off offset:1024
	global_store_dword v[100:101], v185, off offset:1152
	global_store_dword v[100:101], v186, off offset:1280
	global_store_dword v[100:101], v187, off offset:1408
	global_store_dword v[100:101], v188, off offset:1536
	global_store_dword v[100:101], v189, off offset:1664
	global_store_dword v[100:101], v190, off offset:1792
	global_store_dword v[100:101], v191, off offset:1920
	global_store_dword v[102:103], v200, off
	global_store_dword v[102:103], v201, off offset:128
	global_store_dword v[102:103], v202, off offset:256
	global_store_dword v[102:103], v203, off offset:384
	global_store_dword v[102:103], v204, off offset:512
	global_store_dword v[102:103], v205, off offset:640
	global_store_dword v[102:103], v206, off offset:768
	global_store_dword v[102:103], v207, off offset:896
	global_store_dword v[102:103], v208, off offset:1024
	global_store_dword v[102:103], v209, off offset:1152
	global_store_dword v[102:103], v210, off offset:1280
	global_store_dword v[102:103], v211, off offset:1408
	global_store_dword v[102:103], v212, off offset:1536
	global_store_dword v[102:103], v213, off offset:1664
	global_store_dword v[102:103], v214, off offset:1792
	global_store_dword v[102:103], v215, off offset:1920
	s_waitcnt lgkmcnt(0)
	s_barrier
	s_nop 0
	v_readfirstlane_b32 s4, v193
	s_ashr_i32 s1, s4, 6
	v_and_b32_e32 v194, 31, v193
	s_lshl_b32 s12, s1, 5
	v_or_b32_e32 v14, s12, v194
	v_ashrrev_i32_e32 v15, 31, v14
	v_bfe_u32 v220, v193, 5, 1
	v_lshlrev_b64 v[2:3], 8, v[14:15]
	v_lshl_add_u64 v[2:3], s[92:93], 0, v[2:3]
	v_lshlrev_b32_e32 v0, 4, v220
	v_lshl_add_u64 v[6:7], v[2:3], 0, v[0:1]
	flat_load_dwordx4 v[180:183], v[6:7]
	flat_load_dwordx4 v[176:179], v[6:7] offset:32
	flat_load_dwordx4 v[172:175], v[6:7] offset:64
	flat_load_dwordx4 v[168:171], v[6:7] offset:96
	flat_load_dwordx4 v[164:167], v[6:7] offset:128
	flat_load_dwordx4 v[160:163], v[6:7] offset:160
	flat_load_dwordx4 v[2:5], v[6:7] offset:192
	s_lshl_b32 s2, s1, 11
	v_and_b32_e32 v195, 63, v193
	s_add_i32 s2, s2, 0
	s_add_i32 s2, s2, 0x10800
	v_lshlrev_b32_e32 v68, 4, v195
	v_add_u32_e32 v221, s2, v68
	s_lshl_b32 s13, s1, 3
	v_mov_b32_e32 v15, v193
	s_add_i32 s14, s13, s90
	s_add_i32 s13, s13, s10
	s_waitcnt vmcnt(0) lgkmcnt(0)
	ds_write_b128 v221, v[2:5]
	flat_load_dwordx4 v[2:5], v[6:7] offset:224
	s_waitcnt vmcnt(0) lgkmcnt(0)
	ds_write_b128 v221, v[2:5] offset:1024
	v_lshl_add_u64 v[2:3], s[6:7], 0, v[10:11]
	v_mov_b32_e32 v4, v193
	v_readfirstlane_b32 s1, v3
	v_readfirstlane_b32 s40, v2
	s_and_b32 s41, s1, 0xffff
	v_lshlrev_b32_e32 v12, 4, v4
	v_add_u32_e32 v13, 0x2000, v12
	v_lshl_add_u64 v[10:11], s[8:9], 0, v[10:11]
	s_nop 0
	buffer_load_dwordx4 v[6:9], v12, s[40:43], 0 offen sc1
	buffer_load_dwordx4 v[2:5], v13, s[40:43], 0 offen sc1
	v_readfirstlane_b32 s1, v11
	v_readfirstlane_b32 s40, v10
	s_and_b32 s41, s1, 0xffff
	s_nop 3
	buffer_load_dwordx4 v[64:67], v12, s[40:43], 0 offen sc1
	s_nop 0
	buffer_load_dwordx4 v[10:13], v13, s[40:43], 0 offen sc1
	s_waitcnt vmcnt(0)
	s_cmp_gt_i32 s18, 0
	v_ashrrev_i32_e32 v18, 31, v15
	v_lshrrev_b32_e32 v18, 28, v18
	v_add_u32_e32 v18, v15, v18
	v_lshlrev_b32_e32 v19, 4, v18
	v_and_b32_e32 v19, 0xffffff00, v19
	v_lshlrev_b32_e32 v20, 4, v15
	v_sub_u32_e32 v21, v20, v19
	v_bitop3_b32 v18, v21, v18, s73 bitop3:0x78
	v_add3_u32 v18, 0, v19, v18
	v_and_b32_e32 v20, 48, v20
	s_cselect_b64 s[2:3], -1, 0
	s_cmp_lt_i32 s18, 1
	s_waitcnt vmcnt(3)
	ds_write_b128 v18, v[6:9] offset:32768
	v_add_u32_e32 v18, 0x200, v15
	v_ashrrev_i32_e32 v19, 31, v18
	v_lshrrev_b32_e32 v19, 28, v19
	v_add_u32_e32 v19, v18, v19
	v_lshlrev_b32_e32 v21, 4, v19
	v_and_b32_e32 v21, 0xffffff00, v21
	v_lshlrev_b32_e32 v18, 4, v18
	v_sub_u32_e32 v18, v18, v21
	v_bitop3_b32 v18, v18, v19, s73 bitop3:0x78
	v_add3_u32 v18, 0, v21, v18
	s_waitcnt vmcnt(2)
	ds_write_b128 v18, v[2:5] offset:32768
	v_ashrrev_i32_e32 v18, 4, v15
	v_and_b32_e32 v19, 0xfffff0, v18
	v_lshlrev_b32_e32 v21, 1, v18
	v_and_or_b32 v19, v21, 8, v19
	v_lshrrev_b32_e32 v21, 1, v18
	v_lshrrev_b32_e32 v19, 1, v19
	v_bfe_u32 v15, v15, 2, 2
	v_and_b32_e32 v22, 3, v18
	v_or_b32_e32 v19, v19, v15
	v_and_or_b32 v21, v21, 4, v22
	v_lshlrev_b32_e32 v19, 9, v19
	v_lshl_add_u32 v21, v21, 6, 0
	v_add3_u32 v19, v21, v19, v20
	v_add_u32_e32 v18, 32, v18
	s_waitcnt vmcnt(1)
	ds_write_b128 v19, v[64:67]
	v_and_b32_e32 v19, 0xfffff0, v18
	v_lshlrev_b32_e32 v18, 1, v18
	v_and_or_b32 v18, v18, 8, v19
	v_lshrrev_b32_e32 v18, 1, v18
	v_or_b32_e32 v15, v18, v15
	v_lshlrev_b32_e32 v15, 9, v15
	v_add3_u32 v15, v21, v15, v20
	s_waitcnt vmcnt(0)
	ds_write_b128 v15, v[10:13]
	s_cbranch_scc1 .LBB0_1996
	v_lshlrev_b32_e32 v2, 13, v17
	v_lshlrev_b32_e32 v2, 1, v2
	v_add_u32_e32 v10, 0x4000, v2
	v_mov_b32_e32 v11, v1
	v_lshl_add_u64 v[2:3], s[6:7], 0, v[10:11]
	v_mov_b32_e32 v4, v193
	v_readfirstlane_b32 s1, v3
	v_lshl_add_u64 v[10:11], s[8:9], 0, v[10:11]
	v_readfirstlane_b32 s40, v2
	s_and_b32 s41, s1, 0xffff
	v_lshlrev_b32_e32 v12, 4, v4
	v_readfirstlane_b32 s1, v11
	v_add_u32_e32 v13, 0x2000, v12
	s_nop 0
	buffer_load_dwordx4 v[6:9], v12, s[40:43], 0 offen sc1
	buffer_load_dwordx4 v[2:5], v13, s[40:43], 0 offen sc1
	v_readfirstlane_b32 s40, v10
	s_and_b32 s41, s1, 0xffff
	s_nop 3
	buffer_load_dwordx4 v[64:67], v12, s[40:43], 0 offen sc1
	s_nop 0
	buffer_load_dwordx4 v[10:13], v13, s[40:43], 0 offen sc1

.LBB0_2057:
	s_or_b64 exec, exec, s[0:1]
	v_lshlrev_b32_e32 v10, 2, v220
	v_readlane_b32 s0, v255, 1
	v_add_u32_e32 v4, s12, v10
	v_ashrrev_i32_e32 v195, 31, v194
	v_readlane_b32 s1, v255, 2
	v_ashrrev_i32_e32 v5, 31, v4
	v_lshlrev_b64 v[6:7], 9, v[4:5]
	v_lshl_add_u64 v[2:3], v[194:195], 2, s[0:1]
	s_waitcnt lgkmcnt(0)
	v_lshl_add_u64 v[6:7], v[2:3], 0, v[6:7]
	v_add_co_u32_e32 v98, vcc, 0x1000, v6
	s_nop 1
	v_addc_co_u32_e32 v99, vcc, 0, v7, vcc
	v_add_co_u32_e32 v100, vcc, 0x2000, v6
	s_nop 1
	v_addc_co_u32_e32 v101, vcc, 0, v7, vcc
	v_add_co_u32_e32 v102, vcc, 0x3000, v6
	s_nop 1
	v_addc_co_u32_e32 v103, vcc, 0, v7, vcc
	v_lshl_add_u32 v5, v220, 4, s17
	v_lshlrev_b32_e32 v0, 2, v194
	v_readlane_b32 s0, v254, 15
	v_lshl_add_u32 v0, v220, 7, v0
	v_readlane_b32 s1, v254, 16
	v_xor_b32_e32 v0, 4, v0
	v_and_b32_e32 v8, 1, v194
	s_lshl_b64 s[0:1], s[0:1], 12
	v_readlane_b32 s2, v254, 25
	v_cmp_eq_u32_e32 vcc, 0, v8
	v_ashrrev_i32_e32 v8, 2, v4
	s_add_u32 s0, s2, s0
	v_readlane_b32 s2, v254, 27
	v_ashrrev_i32_e32 v9, 31, v8
	s_addc_u32 s1, s2, s1
	v_lshlrev_b64 v[8:9], 12, v[8:9]
	v_lshl_add_u64 v[8:9], s[0:1], 0, v[8:9]
	v_lshl_add_u64 v[8:9], v[194:195], 1, v[8:9]
	ds_read_b128 v[104:107], v5
	ds_read_b128 v[108:111], v5 offset:32
	ds_read_b128 v[112:115], v5 offset:64
	ds_read_b128 v[116:119], v5 offset:96
	s_mov_b64 s[2:3], 0x2000
	v_lshl_add_u64 v[120:121], v[8:9], 0, s[2:3]
	s_mov_b64 s[2:3], 0x4000
	v_lshl_add_u64 v[122:123], v[8:9], 0, s[2:3]
	s_mov_b64 s[2:3], 0x6000
	v_lshl_add_u64 v[124:125], v[8:9], 0, s[2:3]
	global_load_dword v144, v[6:7], off
	global_load_dword v145, v[6:7], off offset:128
	global_load_dword v146, v[6:7], off offset:256
	global_load_dword v147, v[6:7], off offset:384
	global_load_dword v148, v[6:7], off offset:512
	global_load_dword v149, v[6:7], off offset:640
	global_load_dword v150, v[6:7], off offset:768
	global_load_dword v151, v[6:7], off offset:896
	global_load_dword v152, v[6:7], off offset:1024
	global_load_dword v153, v[6:7], off offset:1152
	global_load_dword v154, v[6:7], off offset:1280
	global_load_dword v155, v[6:7], off offset:1408
	global_load_dword v156, v[6:7], off offset:1536
	global_load_dword v157, v[6:7], off offset:1664
	global_load_dword v158, v[6:7], off offset:1792
	global_load_dword v159, v[6:7], off offset:1920
	global_load_dword v160, v[98:99], off
	global_load_dword v161, v[98:99], off offset:128
	global_load_dword v162, v[98:99], off offset:256
	global_load_dword v163, v[98:99], off offset:384
	global_load_dword v164, v[98:99], off offset:512
	global_load_dword v165, v[98:99], off offset:640
	global_load_dword v166, v[98:99], off offset:768
	global_load_dword v167, v[98:99], off offset:896
	global_load_dword v168, v[98:99], off offset:1024
	global_load_dword v169, v[98:99], off offset:1152
	global_load_dword v170, v[98:99], off offset:1280
	global_load_dword v171, v[98:99], off offset:1408
	global_load_dword v172, v[98:99], off offset:1536
	global_load_dword v173, v[98:99], off offset:1664
	global_load_dword v174, v[98:99], off offset:1792
	global_load_dword v175, v[98:99], off offset:1920
	global_load_dword v176, v[100:101], off
	global_load_dword v177, v[100:101], off offset:128
	global_load_dword v178, v[100:101], off offset:256
	global_load_dword v179, v[100:101], off offset:384
	global_load_dword v180, v[100:101], off offset:512
	global_load_dword v181, v[100:101], off offset:640
	global_load_dword v182, v[100:101], off offset:768
	global_load_dword v183, v[100:101], off offset:896
	global_load_dword v184, v[100:101], off offset:1024
	global_load_dword v185, v[100:101], off offset:1152
	global_load_dword v186, v[100:101], off offset:1280
	global_load_dword v187, v[100:101], off offset:1408
	global_load_dword v188, v[100:101], off offset:1536
	global_load_dword v189, v[100:101], off offset:1664
	global_load_dword v190, v[100:101], off offset:1792
	global_load_dword v191, v[100:101], off offset:1920
	global_load_dword v200, v[102:103], off
	global_load_dword v201, v[102:103], off offset:128
	global_load_dword v202, v[102:103], off offset:256
	global_load_dword v203, v[102:103], off offset:384
	global_load_dword v204, v[102:103], off offset:512
	global_load_dword v205, v[102:103], off offset:640
	global_load_dword v206, v[102:103], off offset:768
	global_load_dword v207, v[102:103], off offset:896
	global_load_dword v208, v[102:103], off offset:1024
	global_load_dword v209, v[102:103], off offset:1152
	global_load_dword v210, v[102:103], off offset:1280
	global_load_dword v211, v[102:103], off offset:1408
	global_load_dword v212, v[102:103], off offset:1536
	global_load_dword v213, v[102:103], off offset:1664
	global_load_dword v214, v[102:103], off offset:1792
	global_load_dword v215, v[102:103], off offset:1920
	s_waitcnt vmcnt(32) lgkmcnt(0)
	v_fmac_f32_e32 v144, v80, v104
	v_fmac_f32_e32 v145, v64, v104
	v_fmac_f32_e32 v146, v48, v104
	v_fmac_f32_e32 v147, v32, v104
	v_fmac_f32_e32 v148, v81, v105
	v_fmac_f32_e32 v149, v65, v105
	v_fmac_f32_e32 v150, v49, v105
	v_fmac_f32_e32 v151, v33, v105
	v_fmac_f32_e32 v152, v82, v106
	v_fmac_f32_e32 v153, v66, v106
	v_fmac_f32_e32 v154, v50, v106
	v_fmac_f32_e32 v155, v34, v106
	v_fmac_f32_e32 v156, v83, v107
	v_fmac_f32_e32 v157, v67, v107
	v_fmac_f32_e32 v158, v51, v107
	v_fmac_f32_e32 v159, v35, v107
	v_fmac_f32_e32 v160, v84, v108
	v_fmac_f32_e32 v161, v68, v108
	v_fmac_f32_e32 v162, v52, v108
	v_fmac_f32_e32 v163, v36, v108
	v_fmac_f32_e32 v164, v85, v109
	v_fmac_f32_e32 v165, v69, v109
	v_fmac_f32_e32 v166, v53, v109
	v_fmac_f32_e32 v167, v37, v109
	v_fmac_f32_e32 v168, v86, v110
	v_fmac_f32_e32 v169, v70, v110
	v_fmac_f32_e32 v170, v54, v110
	v_fmac_f32_e32 v171, v38, v110
	v_fmac_f32_e32 v172, v87, v111
	v_fmac_f32_e32 v173, v71, v111
	v_fmac_f32_e32 v174, v55, v111
	v_fmac_f32_e32 v175, v39, v111
	ds_bpermute_b32 v216, v0, v144
	ds_bpermute_b32 v217, v0, v145
	ds_bpermute_b32 v218, v0, v146
	ds_bpermute_b32 v219, v0, v147
	ds_bpermute_b32 v220, v0, v148
	ds_bpermute_b32 v221, v0, v149
	ds_bpermute_b32 v222, v0, v150
	ds_bpermute_b32 v223, v0, v151
	ds_bpermute_b32 v224, v0, v152
	ds_bpermute_b32 v225, v0, v153
	ds_bpermute_b32 v226, v0, v154
	ds_bpermute_b32 v227, v0, v155
	ds_bpermute_b32 v228, v0, v156
	ds_bpermute_b32 v229, v0, v157
	ds_bpermute_b32 v230, v0, v158
	ds_bpermute_b32 v231, v0, v159
	ds_bpermute_b32 v232, v0, v160
	ds_bpermute_b32 v233, v0, v161
	ds_bpermute_b32 v234, v0, v162
	ds_bpermute_b32 v235, v0, v163
	ds_bpermute_b32 v236, v0, v164
	ds_bpermute_b32 v237, v0, v165
	ds_bpermute_b32 v126, v0, v166
	ds_bpermute_b32 v127, v0, v167
	ds_bpermute_b32 v128, v0, v168
	ds_bpermute_b32 v129, v0, v169
	ds_bpermute_b32 v130, v0, v170
	ds_bpermute_b32 v131, v0, v171
	ds_bpermute_b32 v132, v0, v172
	ds_bpermute_b32 v133, v0, v173
	ds_bpermute_b32 v134, v0, v174
	ds_bpermute_b32 v135, v0, v175
	s_waitcnt lgkmcnt(0)
	v_cvt_pk_bf16_f32 v144, v144, v216
	v_cvt_pk_bf16_f32 v145, v145, v217
	v_cvt_pk_bf16_f32 v146, v146, v218
	v_cvt_pk_bf16_f32 v147, v147, v219
	v_cvt_pk_bf16_f32 v148, v148, v220
	v_cvt_pk_bf16_f32 v149, v149, v221
	v_cvt_pk_bf16_f32 v150, v150, v222
	v_cvt_pk_bf16_f32 v151, v151, v223
	v_cvt_pk_bf16_f32 v152, v152, v224
	v_cvt_pk_bf16_f32 v153, v153, v225
	v_cvt_pk_bf16_f32 v154, v154, v226
	v_cvt_pk_bf16_f32 v155, v155, v227
	v_cvt_pk_bf16_f32 v156, v156, v228
	v_cvt_pk_bf16_f32 v157, v157, v229
	v_cvt_pk_bf16_f32 v158, v158, v230
	v_cvt_pk_bf16_f32 v159, v159, v231
	v_cvt_pk_bf16_f32 v160, v160, v232
	v_cvt_pk_bf16_f32 v161, v161, v233
	v_cvt_pk_bf16_f32 v162, v162, v234
	v_cvt_pk_bf16_f32 v163, v163, v235
	v_cvt_pk_bf16_f32 v164, v164, v236
	v_cvt_pk_bf16_f32 v165, v165, v237
	v_cvt_pk_bf16_f32 v166, v166, v126
	v_cvt_pk_bf16_f32 v167, v167, v127
	v_cvt_pk_bf16_f32 v168, v168, v128
	v_cvt_pk_bf16_f32 v169, v169, v129
	v_cvt_pk_bf16_f32 v170, v170, v130
	v_cvt_pk_bf16_f32 v171, v171, v131
	v_cvt_pk_bf16_f32 v172, v172, v132
	v_cvt_pk_bf16_f32 v173, v173, v133
	v_cvt_pk_bf16_f32 v174, v174, v134
	v_cvt_pk_bf16_f32 v175, v175, v135
	s_and_saveexec_b64 s[2:3], vcc
	global_store_dword v[8:9], v144, off offset:3072
	global_store_dword v[8:9], v145, off offset:3136
	global_store_dword v[8:9], v146, off offset:3200
	global_store_dword v[8:9], v147, off offset:3264
	global_store_dword v[8:9], v148, off offset:3328
	global_store_dword v[8:9], v149, off offset:3392
	global_store_dword v[8:9], v150, off offset:3456
	global_store_dword v[8:9], v151, off offset:3520
	global_store_dword v[8:9], v152, off offset:3584
	global_store_dword v[8:9], v153, off offset:3648
	global_store_dword v[8:9], v154, off offset:3712
	global_store_dword v[8:9], v155, off offset:3776
	global_store_dword v[8:9], v156, off offset:3840
	global_store_dword v[8:9], v157, off offset:3904
	global_store_dword v[8:9], v158, off offset:3968
	global_store_dword v[8:9], v159, off offset:4032
	global_store_dword v[120:121], v160, off offset:3072
	global_store_dword v[120:121], v161, off offset:3136
	global_store_dword v[120:121], v162, off offset:3200
	global_store_dword v[120:121], v163, off offset:3264
	global_store_dword v[120:121], v164, off offset:3328
	global_store_dword v[120:121], v165, off offset:3392
	global_store_dword v[120:121], v166, off offset:3456
	global_store_dword v[120:121], v167, off offset:3520
	global_store_dword v[120:121], v168, off offset:3584
	global_store_dword v[120:121], v169, off offset:3648
	global_store_dword v[120:121], v170, off offset:3712
	global_store_dword v[120:121], v171, off offset:3776
	global_store_dword v[120:121], v172, off offset:3840
	global_store_dword v[120:121], v173, off offset:3904
	global_store_dword v[120:121], v174, off offset:3968
	global_store_dword v[120:121], v175, off offset:4032
	s_or_b64 exec, exec, s[2:3]
	s_waitcnt vmcnt(32)
	v_fmac_f32_e32 v176, v88, v112
	v_fmac_f32_e32 v177, v72, v112
	v_fmac_f32_e32 v178, v56, v112
	v_fmac_f32_e32 v179, v40, v112
	v_fmac_f32_e32 v180, v89, v113
	v_fmac_f32_e32 v181, v73, v113
	v_fmac_f32_e32 v182, v57, v113
	v_fmac_f32_e32 v183, v41, v113
	v_fmac_f32_e32 v184, v90, v114
	v_fmac_f32_e32 v185, v74, v114
	v_fmac_f32_e32 v186, v58, v114
	v_fmac_f32_e32 v187, v42, v114
	v_fmac_f32_e32 v188, v91, v115
	v_fmac_f32_e32 v189, v75, v115
	v_fmac_f32_e32 v190, v59, v115
	v_fmac_f32_e32 v191, v43, v115
	v_fmac_f32_e32 v200, v92, v116
	v_fmac_f32_e32 v201, v76, v116
	v_fmac_f32_e32 v202, v60, v116
	v_fmac_f32_e32 v203, v44, v116
	v_fmac_f32_e32 v204, v93, v117
	v_fmac_f32_e32 v205, v77, v117
	v_fmac_f32_e32 v206, v61, v117
	v_fmac_f32_e32 v207, v45, v117
	v_fmac_f32_e32 v208, v94, v118
	v_fmac_f32_e32 v209, v78, v118
	v_fmac_f32_e32 v210, v62, v118
	v_fmac_f32_e32 v211, v46, v118
	v_fmac_f32_e32 v212, v95, v119
	v_fmac_f32_e32 v213, v79, v119
	v_fmac_f32_e32 v214, v63, v119
	v_fmac_f32_e32 v215, v47, v119
	ds_bpermute_b32 v216, v0, v176
	ds_bpermute_b32 v217, v0, v177
	ds_bpermute_b32 v218, v0, v178
	ds_bpermute_b32 v219, v0, v179
	ds_bpermute_b32 v220, v0, v180
	ds_bpermute_b32 v221, v0, v181
	ds_bpermute_b32 v222, v0, v182
	ds_bpermute_b32 v223, v0, v183
	ds_bpermute_b32 v224, v0, v184
	ds_bpermute_b32 v225, v0, v185
	ds_bpermute_b32 v226, v0, v186
	ds_bpermute_b32 v227, v0, v187
	ds_bpermute_b32 v228, v0, v188
	ds_bpermute_b32 v229, v0, v189
	ds_bpermute_b32 v230, v0, v190
	ds_bpermute_b32 v231, v0, v191
	ds_bpermute_b32 v232, v0, v200
	ds_bpermute_b32 v233, v0, v201
	ds_bpermute_b32 v234, v0, v202
	ds_bpermute_b32 v235, v0, v203
	ds_bpermute_b32 v236, v0, v204
	ds_bpermute_b32 v237, v0, v205
	ds_bpermute_b32 v126, v0, v206
	ds_bpermute_b32 v127, v0, v207
	ds_bpermute_b32 v128, v0, v208
	ds_bpermute_b32 v129, v0, v209
	ds_bpermute_b32 v130, v0, v210
	ds_bpermute_b32 v131, v0, v211
	ds_bpermute_b32 v132, v0, v212
	ds_bpermute_b32 v133, v0, v213
	ds_bpermute_b32 v134, v0, v214
	ds_bpermute_b32 v135, v0, v215
	s_waitcnt lgkmcnt(0)
	v_cvt_pk_bf16_f32 v176, v176, v216
	v_cvt_pk_bf16_f32 v177, v177, v217
	v_cvt_pk_bf16_f32 v178, v178, v218
	v_cvt_pk_bf16_f32 v179, v179, v219
	v_cvt_pk_bf16_f32 v180, v180, v220
	v_cvt_pk_bf16_f32 v181, v181, v221
	v_cvt_pk_bf16_f32 v182, v182, v222
	v_cvt_pk_bf16_f32 v183, v183, v223
	v_cvt_pk_bf16_f32 v184, v184, v224
	v_cvt_pk_bf16_f32 v185, v185, v225
	v_cvt_pk_bf16_f32 v186, v186, v226
	v_cvt_pk_bf16_f32 v187, v187, v227
	v_cvt_pk_bf16_f32 v188, v188, v228
	v_cvt_pk_bf16_f32 v189, v189, v229
	v_cvt_pk_bf16_f32 v190, v190, v230
	v_cvt_pk_bf16_f32 v191, v191, v231
	v_cvt_pk_bf16_f32 v200, v200, v232
	v_cvt_pk_bf16_f32 v201, v201, v233
	v_cvt_pk_bf16_f32 v202, v202, v234
	v_cvt_pk_bf16_f32 v203, v203, v235
	v_cvt_pk_bf16_f32 v204, v204, v236
	v_cvt_pk_bf16_f32 v205, v205, v237
	v_cvt_pk_bf16_f32 v206, v206, v126
	v_cvt_pk_bf16_f32 v207, v207, v127
	v_cvt_pk_bf16_f32 v208, v208, v128
	v_cvt_pk_bf16_f32 v209, v209, v129
	v_cvt_pk_bf16_f32 v210, v210, v130
	v_cvt_pk_bf16_f32 v211, v211, v131
	v_cvt_pk_bf16_f32 v212, v212, v132
	v_cvt_pk_bf16_f32 v213, v213, v133
	v_cvt_pk_bf16_f32 v214, v214, v134
	v_cvt_pk_bf16_f32 v215, v215, v135
	s_and_saveexec_b64 s[2:3], vcc
	global_store_dword v[122:123], v176, off offset:3072
	global_store_dword v[122:123], v177, off offset:3136
	global_store_dword v[122:123], v178, off offset:3200
	global_store_dword v[122:123], v179, off offset:3264
	global_store_dword v[122:123], v180, off offset:3328
	global_store_dword v[122:123], v181, off offset:3392
	global_store_dword v[122:123], v182, off offset:3456
	global_store_dword v[122:123], v183, off offset:3520
	global_store_dword v[122:123], v184, off offset:3584
	global_store_dword v[122:123], v185, off offset:3648
	global_store_dword v[122:123], v186, off offset:3712
	global_store_dword v[122:123], v187, off offset:3776
	global_store_dword v[122:123], v188, off offset:3840
	global_store_dword v[122:123], v189, off offset:3904
	global_store_dword v[122:123], v190, off offset:3968
	global_store_dword v[122:123], v191, off offset:4032
	global_store_dword v[124:125], v200, off offset:3072
	global_store_dword v[124:125], v201, off offset:3136
	global_store_dword v[124:125], v202, off offset:3200
	global_store_dword v[124:125], v203, off offset:3264
	global_store_dword v[124:125], v204, off offset:3328
	global_store_dword v[124:125], v205, off offset:3392
	global_store_dword v[124:125], v206, off offset:3456
	global_store_dword v[124:125], v207, off offset:3520
	global_store_dword v[124:125], v208, off offset:3584
	global_store_dword v[124:125], v209, off offset:3648
	global_store_dword v[124:125], v210, off offset:3712
	global_store_dword v[124:125], v211, off offset:3776
	global_store_dword v[124:125], v212, off offset:3840
	global_store_dword v[124:125], v213, off offset:3904
	global_store_dword v[124:125], v214, off offset:3968
	global_store_dword v[124:125], v215, off offset:4032
	s_or_b64 exec, exec, s[2:3]
	s_mov_b32 s2, -1
	s_waitcnt lgkmcnt(0)
	s_barrier

.LBB0_2213:
	s_or_b64 exec, exec, s[0:1]
	s_waitcnt lgkmcnt(0)
	v_lshl_add_u32 v6, v15, 4, s10
	s_lshl_b32 s0, s7, 12
	v_readlane_b32 s1, v254, 25
	s_add_u32 s0, s1, s0
	v_readlane_b32 s1, v254, 27
	v_lshlrev_b32_e32 v3, 2, v14
	s_addc_u32 s1, s1, 0
	v_lshl_add_u32 v3, v15, 7, v3
	s_add_u32 s2, s0, s4
	v_xor_b32_e32 v0, 4, v3
	s_addc_u32 s3, s1, s5
	s_ashr_i32 s7, s6, 31
	s_lshl_b64 s[0:1], s[6:7], 12
	v_lshlrev_b32_e32 v2, 2, v15
	v_and_b32_e32 v3, 1, v14
	s_add_u32 s0, s2, s0
	v_cmp_eq_u32_e32 vcc, 0, v3
	s_addc_u32 s1, s3, s1
	ds_read_b128 v[104:107], v6
	ds_read_b128 v[108:111], v6 offset:32
	ds_read_b128 v[112:115], v6 offset:64
	ds_read_b128 v[116:119], v6 offset:96
	v_lshlrev_b32_e32 v120, 12, v2
	v_lshl_add_u32 v120, v14, 1, v120
	v_add_u32_e32 v121, 0x1000, v120
	v_add_u32_e32 v122, 0x2000, v120
	v_add_u32_e32 v123, 0x3000, v120
	v_add_u32_e32 v124, 0x8000, v120
	v_add_u32_e32 v125, 0x9000, v120
	v_add_u32_e32 v126, 0xa000, v120
	v_add_u32_e32 v127, 0xb000, v120
	v_add_u32_e32 v128, 0x10000, v120
	v_add_u32_e32 v129, 0x11000, v120
	v_add_u32_e32 v130, 0x12000, v120
	v_add_u32_e32 v131, 0x13000, v120
	v_add_u32_e32 v132, 0x18000, v120
	v_add_u32_e32 v133, 0x19000, v120
	v_add_u32_e32 v134, 0x1a000, v120
	v_add_u32_e32 v135, 0x1b000, v120
	s_waitcnt lgkmcnt(0)
	v_rcp_f32_e32 v104, v104
	v_rcp_f32_e32 v105, v105
	v_rcp_f32_e32 v106, v106
	v_rcp_f32_e32 v107, v107
	v_rcp_f32_e32 v108, v108
	v_rcp_f32_e32 v109, v109
	v_rcp_f32_e32 v110, v110
	v_rcp_f32_e32 v111, v111
	v_rcp_f32_e32 v112, v112
	v_rcp_f32_e32 v113, v113
	v_rcp_f32_e32 v114, v114
	v_rcp_f32_e32 v115, v115
	v_rcp_f32_e32 v116, v116
	v_rcp_f32_e32 v117, v117
	v_rcp_f32_e32 v118, v118
	v_rcp_f32_e32 v119, v119
	s_nop 0
	v_mul_f32_e32 v50, v50, v104
	v_mul_f32_e32 v66, v66, v104
	v_mul_f32_e32 v34, v34, v104
	v_mul_f32_e32 v18, v18, v104
	v_mul_f32_e32 v51, v51, v105
	v_mul_f32_e32 v67, v67, v105
	v_mul_f32_e32 v35, v35, v105
	v_mul_f32_e32 v19, v19, v105
	v_mul_f32_e32 v52, v52, v106
	v_mul_f32_e32 v68, v68, v106
	v_mul_f32_e32 v36, v36, v106
	v_mul_f32_e32 v20, v20, v106
	v_mul_f32_e32 v53, v53, v107
	v_mul_f32_e32 v69, v69, v107
	v_mul_f32_e32 v37, v37, v107
	v_mul_f32_e32 v21, v21, v107
	v_mul_f32_e32 v54, v54, v108
	v_mul_f32_e32 v70, v70, v108
	v_mul_f32_e32 v38, v38, v108
	v_mul_f32_e32 v22, v22, v108
	v_mul_f32_e32 v55, v55, v109
	v_mul_f32_e32 v71, v71, v109
	v_mul_f32_e32 v39, v39, v109
	v_mul_f32_e32 v23, v23, v109
	v_mul_f32_e32 v56, v56, v110
	v_mul_f32_e32 v72, v72, v110
	v_mul_f32_e32 v40, v40, v110
	v_mul_f32_e32 v24, v24, v110
	v_mul_f32_e32 v57, v57, v111
	v_mul_f32_e32 v73, v73, v111
	v_mul_f32_e32 v41, v41, v111
	v_mul_f32_e32 v25, v25, v111
	ds_bpermute_b32 v144, v0, v50
	ds_bpermute_b32 v145, v0, v66
	ds_bpermute_b32 v146, v0, v34
	ds_bpermute_b32 v147, v0, v18
	ds_bpermute_b32 v148, v0, v51
	ds_bpermute_b32 v149, v0, v67
	ds_bpermute_b32 v150, v0, v35
	ds_bpermute_b32 v151, v0, v19
	ds_bpermute_b32 v152, v0, v52
	ds_bpermute_b32 v153, v0, v68
	ds_bpermute_b32 v154, v0, v36
	ds_bpermute_b32 v155, v0, v20
	ds_bpermute_b32 v156, v0, v53
	ds_bpermute_b32 v157, v0, v69
	ds_bpermute_b32 v158, v0, v37
	ds_bpermute_b32 v159, v0, v21
	ds_bpermute_b32 v160, v0, v54
	ds_bpermute_b32 v161, v0, v70
	ds_bpermute_b32 v162, v0, v38
	ds_bpermute_b32 v163, v0, v22
	ds_bpermute_b32 v164, v0, v55
	ds_bpermute_b32 v165, v0, v71
	ds_bpermute_b32 v166, v0, v39
	ds_bpermute_b32 v167, v0, v23
	ds_bpermute_b32 v168, v0, v56
	ds_bpermute_b32 v169, v0, v72
	ds_bpermute_b32 v170, v0, v40
	ds_bpermute_b32 v171, v0, v24
	ds_bpermute_b32 v172, v0, v57
	ds_bpermute_b32 v173, v0, v73
	ds_bpermute_b32 v174, v0, v41
	ds_bpermute_b32 v175, v0, v25
	s_waitcnt lgkmcnt(0)
	v_cvt_pk_bf16_f32 v50, v50, v144
	v_cvt_pk_bf16_f32 v66, v66, v145
	v_cvt_pk_bf16_f32 v34, v34, v146
	v_cvt_pk_bf16_f32 v18, v18, v147
	v_cvt_pk_bf16_f32 v51, v51, v148
	v_cvt_pk_bf16_f32 v67, v67, v149
	v_cvt_pk_bf16_f32 v35, v35, v150
	v_cvt_pk_bf16_f32 v19, v19, v151
	v_cvt_pk_bf16_f32 v52, v52, v152
	v_cvt_pk_bf16_f32 v68, v68, v153
	v_cvt_pk_bf16_f32 v36, v36, v154
	v_cvt_pk_bf16_f32 v20, v20, v155
	v_cvt_pk_bf16_f32 v53, v53, v156
	v_cvt_pk_bf16_f32 v69, v69, v157
	v_cvt_pk_bf16_f32 v37, v37, v158
	v_cvt_pk_bf16_f32 v21, v21, v159
	v_cvt_pk_bf16_f32 v54, v54, v160
	v_cvt_pk_bf16_f32 v70, v70, v161
	v_cvt_pk_bf16_f32 v38, v38, v162
	v_cvt_pk_bf16_f32 v22, v22, v163
	v_cvt_pk_bf16_f32 v55, v55, v164
	v_cvt_pk_bf16_f32 v71, v71, v165
	v_cvt_pk_bf16_f32 v39, v39, v166
	v_cvt_pk_bf16_f32 v23, v23, v167
	v_cvt_pk_bf16_f32 v56, v56, v168
	v_cvt_pk_bf16_f32 v72, v72, v169
	v_cvt_pk_bf16_f32 v40, v40, v170
	v_cvt_pk_bf16_f32 v24, v24, v171
	v_cvt_pk_bf16_f32 v57, v57, v172
	v_cvt_pk_bf16_f32 v73, v73, v173
	v_cvt_pk_bf16_f32 v41, v41, v174
	v_cvt_pk_bf16_f32 v25, v25, v175
	s_and_saveexec_b64 s[2:3], vcc
	global_store_dword v120, v50, s[0:1]
	global_store_dword v120, v66, s[0:1] offset:64
	global_store_dword v120, v34, s[0:1] offset:128
	global_store_dword v120, v18, s[0:1] offset:192
	global_store_dword v121, v51, s[0:1]
	global_store_dword v121, v67, s[0:1] offset:64
	global_store_dword v121, v35, s[0:1] offset:128
	global_store_dword v121, v19, s[0:1] offset:192
	global_store_dword v122, v52, s[0:1]
	global_store_dword v122, v68, s[0:1] offset:64
	global_store_dword v122, v36, s[0:1] offset:128
	global_store_dword v122, v20, s[0:1] offset:192
	global_store_dword v123, v53, s[0:1]
	global_store_dword v123, v69, s[0:1] offset:64
	global_store_dword v123, v37, s[0:1] offset:128
	global_store_dword v123, v21, s[0:1] offset:192
	global_store_dword v124, v54, s[0:1]
	global_store_dword v124, v70, s[0:1] offset:64
	global_store_dword v124, v38, s[0:1] offset:128
	global_store_dword v124, v22, s[0:1] offset:192
	global_store_dword v125, v55, s[0:1]
	global_store_dword v125, v71, s[0:1] offset:64
	global_store_dword v125, v39, s[0:1] offset:128
	global_store_dword v125, v23, s[0:1] offset:192
	global_store_dword v126, v56, s[0:1]
	global_store_dword v126, v72, s[0:1] offset:64
	global_store_dword v126, v40, s[0:1] offset:128
	global_store_dword v126, v24, s[0:1] offset:192
	global_store_dword v127, v57, s[0:1]
	global_store_dword v127, v73, s[0:1] offset:64
	global_store_dword v127, v41, s[0:1] offset:128
	global_store_dword v127, v25, s[0:1] offset:192
	s_or_b64 exec, exec, s[2:3]
	v_mul_f32_e32 v58, v58, v112
	v_mul_f32_e32 v74, v74, v112
	v_mul_f32_e32 v42, v42, v112
	v_mul_f32_e32 v26, v26, v112
	v_mul_f32_e32 v59, v59, v113
	v_mul_f32_e32 v75, v75, v113
	v_mul_f32_e32 v43, v43, v113
	v_mul_f32_e32 v27, v27, v113
	v_mul_f32_e32 v60, v60, v114
	v_mul_f32_e32 v76, v76, v114
	v_mul_f32_e32 v44, v44, v114
	v_mul_f32_e32 v28, v28, v114
	v_mul_f32_e32 v61, v61, v115
	v_mul_f32_e32 v77, v77, v115
	v_mul_f32_e32 v45, v45, v115
	v_mul_f32_e32 v29, v29, v115
	v_mul_f32_e32 v62, v62, v116
	v_mul_f32_e32 v78, v78, v116
	v_mul_f32_e32 v46, v46, v116
	v_mul_f32_e32 v30, v30, v116
	v_mul_f32_e32 v63, v63, v117
	v_mul_f32_e32 v79, v79, v117
	v_mul_f32_e32 v47, v47, v117
	v_mul_f32_e32 v31, v31, v117
	v_mul_f32_e32 v64, v64, v118
	v_mul_f32_e32 v80, v80, v118
	v_mul_f32_e32 v48, v48, v118
	v_mul_f32_e32 v32, v32, v118
	v_mul_f32_e32 v65, v65, v119
	v_mul_f32_e32 v81, v81, v119
	v_mul_f32_e32 v49, v49, v119
	v_mul_f32_e32 v33, v33, v119
	ds_bpermute_b32 v144, v0, v58
	ds_bpermute_b32 v145, v0, v74
	ds_bpermute_b32 v146, v0, v42
	ds_bpermute_b32 v147, v0, v26
	ds_bpermute_b32 v148, v0, v59
	ds_bpermute_b32 v149, v0, v75
	ds_bpermute_b32 v150, v0, v43
	ds_bpermute_b32 v151, v0, v27
	ds_bpermute_b32 v152, v0, v60
	ds_bpermute_b32 v153, v0, v76
	ds_bpermute_b32 v154, v0, v44
	ds_bpermute_b32 v155, v0, v28
	ds_bpermute_b32 v156, v0, v61
	ds_bpermute_b32 v157, v0, v77
	ds_bpermute_b32 v158, v0, v45
	ds_bpermute_b32 v159, v0, v29
	ds_bpermute_b32 v160, v0, v62
	ds_bpermute_b32 v161, v0, v78
	ds_bpermute_b32 v162, v0, v46
	ds_bpermute_b32 v163, v0, v30
	ds_bpermute_b32 v164, v0, v63
	ds_bpermute_b32 v165, v0, v79
	ds_bpermute_b32 v166, v0, v47
	ds_bpermute_b32 v167, v0, v31
	ds_bpermute_b32 v168, v0, v64
	ds_bpermute_b32 v169, v0, v80
	ds_bpermute_b32 v170, v0, v48
	ds_bpermute_b32 v171, v0, v32
	ds_bpermute_b32 v172, v0, v65
	ds_bpermute_b32 v173, v0, v81
	ds_bpermute_b32 v174, v0, v49
	ds_bpermute_b32 v175, v0, v33
	s_waitcnt lgkmcnt(0)
	v_cvt_pk_bf16_f32 v58, v58, v144
	v_cvt_pk_bf16_f32 v74, v74, v145
	v_cvt_pk_bf16_f32 v42, v42, v146
	v_cvt_pk_bf16_f32 v26, v26, v147
	v_cvt_pk_bf16_f32 v59, v59, v148
	v_cvt_pk_bf16_f32 v75, v75, v149
	v_cvt_pk_bf16_f32 v43, v43, v150
	v_cvt_pk_bf16_f32 v27, v27, v151
	v_cvt_pk_bf16_f32 v60, v60, v152
	v_cvt_pk_bf16_f32 v76, v76, v153
	v_cvt_pk_bf16_f32 v44, v44, v154
	v_cvt_pk_bf16_f32 v28, v28, v155
	v_cvt_pk_bf16_f32 v61, v61, v156
	v_cvt_pk_bf16_f32 v77, v77, v157
	v_cvt_pk_bf16_f32 v45, v45, v158
	v_cvt_pk_bf16_f32 v29, v29, v159
	v_cvt_pk_bf16_f32 v62, v62, v160
	v_cvt_pk_bf16_f32 v78, v78, v161
	v_cvt_pk_bf16_f32 v46, v46, v162
	v_cvt_pk_bf16_f32 v30, v30, v163
	v_cvt_pk_bf16_f32 v63, v63, v164
	v_cvt_pk_bf16_f32 v79, v79, v165
	v_cvt_pk_bf16_f32 v47, v47, v166
	v_cvt_pk_bf16_f32 v31, v31, v167
	v_cvt_pk_bf16_f32 v64, v64, v168
	v_cvt_pk_bf16_f32 v80, v80, v169
	v_cvt_pk_bf16_f32 v48, v48, v170
	v_cvt_pk_bf16_f32 v32, v32, v171
	v_cvt_pk_bf16_f32 v65, v65, v172
	v_cvt_pk_bf16_f32 v81, v81, v173
	v_cvt_pk_bf16_f32 v49, v49, v174
	v_cvt_pk_bf16_f32 v33, v33, v175
	s_and_saveexec_b64 s[2:3], vcc
	global_store_dword v128, v58, s[0:1]
	global_store_dword v128, v74, s[0:1] offset:64
	global_store_dword v128, v42, s[0:1] offset:128
	global_store_dword v128, v26, s[0:1] offset:192
	global_store_dword v129, v59, s[0:1]
	global_store_dword v129, v75, s[0:1] offset:64
	global_store_dword v129, v43, s[0:1] offset:128
	global_store_dword v129, v27, s[0:1] offset:192
	global_store_dword v130, v60, s[0:1]
	global_store_dword v130, v76, s[0:1] offset:64
	global_store_dword v130, v44, s[0:1] offset:128
	global_store_dword v130, v28, s[0:1] offset:192
	global_store_dword v131, v61, s[0:1]
	global_store_dword v131, v77, s[0:1] offset:64
	global_store_dword v131, v45, s[0:1] offset:128
	global_store_dword v131, v29, s[0:1] offset:192
	global_store_dword v132, v62, s[0:1]
	global_store_dword v132, v78, s[0:1] offset:64
	global_store_dword v132, v46, s[0:1] offset:128
	global_store_dword v132, v30, s[0:1] offset:192
	global_store_dword v133, v63, s[0:1]
	global_store_dword v133, v79, s[0:1] offset:64
	global_store_dword v133, v47, s[0:1] offset:128
	global_store_dword v133, v31, s[0:1] offset:192
	global_store_dword v134, v64, s[0:1]
	global_store_dword v134, v80, s[0:1] offset:64
	global_store_dword v134, v48, s[0:1] offset:128
	global_store_dword v134, v32, s[0:1] offset:192
	global_store_dword v135, v65, s[0:1]
	global_store_dword v135, v81, s[0:1] offset:64
	global_store_dword v135, v49, s[0:1] offset:128
	global_store_dword v135, v33, s[0:1] offset:192
	s_or_b64 exec, exec, s[2:3]
	s_mov_b64 s[0:1], exec
	s_branch .LBB0_1663
